# GEMM K-loops (both): LDS-DMA staging balanced 4/4/4/4 pieces per super-phase instead of 2/6/2/6 (As[b][0] of K-tile u staged in SP1(u-1) instead of SP2(u-2); SP2 waits vmcnt(6))
# speedup vs baseline: 1.0077x; 1.0053x over previous
.LBB0_94:
	s_add_u32 s90, s48, 0xfffc0000
	s_addc_u32 s91, s49, -1
	v_lshl_add_u64 v[198:199], s[90:91], 0, v[152:153]
	s_mov_b32 m0, s77
	s_nop 0
	global_load_lds_dwordx4 v[198:199], off
	v_lshl_add_u64 v[198:199], s[90:91], 0, v[148:149]
	s_mov_b32 m0, s78
	s_nop 0
	global_load_lds_dwordx4 v[198:199], off
	s_add_u32 s60, s48, 0xfffc0080
	s_addc_u32 s61, s49, -1
	s_add_i32 s88, 0, 0x10000
	s_cmp_eq_u32 s87, 12
	s_cselect_b32 vcc_hi, s59, s61
	s_cselect_b32 vcc_lo, s83, s60
	v_add_u32_e32 v2, s88, v182
	s_cselect_b32 s61, s95, s86
	s_cselect_b32 s60, s84, s85
	s_add_i32 s90, 0, 0x14000
	ds_read_b128 v[132:135], v2
	ds_read_b128 v[136:139], v2 offset:1024
	ds_read_b128 v[140:143], v2 offset:2048
	ds_read_b128 v[144:147], v2 offset:3072
	v_add_u32_e32 v2, s90, v182
	ds_read_b128 v[162:165], v2
	ds_read_b128 v[166:169], v2 offset:1024
	ds_read_b128 v[170:173], v2 offset:2048
	ds_read_b128 v[174:177], v2 offset:3072
	v_lshl_add_u64 v[198:199], s[48:49], 0, v[158:159]
	s_add_i32 m0, s73, 0xc000
	ds_read_b128 v[178:181], v185
	ds_read_b128 v[186:189], v185 offset:1024
	ds_read_b128 v[190:193], v185 offset:2048
	ds_read_b128 v[194:197], v185 offset:3072
	ds_read_b128 v[208:211], v185 offset:4096
	ds_read_b128 v[212:215], v185 offset:5120
	ds_read_b128 v[216:219], v185 offset:6144
	ds_read_b128 v[220:223], v185 offset:7168
	global_load_lds_dwordx4 v[198:199], off
	v_lshl_add_u64 v[198:199], s[48:49], 0, v[160:161]
	s_add_i32 m0, s73, 0xe000
	s_nop 0
	global_load_lds_dwordx4 v[198:199], off
	s_waitcnt vmcnt(8)
	s_waitcnt lgkmcnt(0)
	s_barrier
	s_setprio 1
	s_waitcnt lgkmcnt(0)
	v_mfma_f32_16x16x32_bf16 v[128:131], v[132:135], v[178:181], v[128:131]
	v_mfma_f32_16x16x32_bf16 v[120:123], v[140:143], v[178:181], v[120:123]
	v_mfma_f32_16x16x32_bf16 v[112:115], v[132:135], v[190:193], v[112:115]
	v_mfma_f32_16x16x32_bf16 v[84:87], v[140:143], v[190:193], v[84:87]
	v_mfma_f32_16x16x32_bf16 v[104:107], v[132:135], v[208:211], v[104:107]
	v_mfma_f32_16x16x32_bf16 v[72:75], v[140:143], v[208:211], v[72:75]
	v_mfma_f32_16x16x32_bf16 v[96:99], v[132:135], v[216:219], v[96:99]
	v_mfma_f32_16x16x32_bf16 v[88:91], v[140:143], v[216:219], v[88:91]
	v_mfma_f32_16x16x32_bf16 v[128:131], v[136:139], v[186:189], v[128:131]
	v_mfma_f32_16x16x32_bf16 v[120:123], v[144:147], v[186:189], v[120:123]
	v_mfma_f32_16x16x32_bf16 v[112:115], v[136:139], v[194:197], v[112:115]
	v_mfma_f32_16x16x32_bf16 v[84:87], v[144:147], v[194:197], v[84:87]
	v_mfma_f32_16x16x32_bf16 v[104:107], v[136:139], v[212:215], v[104:107]
	v_mfma_f32_16x16x32_bf16 v[72:75], v[144:147], v[212:215], v[72:75]
	v_mfma_f32_16x16x32_bf16 v[96:99], v[136:139], v[220:223], v[96:99]
	v_mfma_f32_16x16x32_bf16 v[88:91], v[144:147], v[220:223], v[88:91]
	s_setprio 0
	s_setprio 1
	v_mfma_f32_16x16x32_bf16 v[124:127], v[162:165], v[178:181], v[124:127]
	v_mfma_f32_16x16x32_bf16 v[116:119], v[170:173], v[178:181], v[116:119]
	v_mfma_f32_16x16x32_bf16 v[108:111], v[162:165], v[190:193], v[108:111]
	v_mfma_f32_16x16x32_bf16 v[76:79], v[170:173], v[190:193], v[76:79]
	v_mfma_f32_16x16x32_bf16 v[100:103], v[162:165], v[208:211], v[100:103]
	v_mfma_f32_16x16x32_bf16 v[68:71], v[170:173], v[208:211], v[68:71]
	v_mfma_f32_16x16x32_bf16 v[92:95], v[162:165], v[216:219], v[92:95]
	v_mfma_f32_16x16x32_bf16 v[80:83], v[170:173], v[216:219], v[80:83]
	v_mfma_f32_16x16x32_bf16 v[124:127], v[166:169], v[186:189], v[124:127]
	v_mfma_f32_16x16x32_bf16 v[116:119], v[174:177], v[186:189], v[116:119]
	v_mfma_f32_16x16x32_bf16 v[108:111], v[166:169], v[194:197], v[108:111]
	v_mfma_f32_16x16x32_bf16 v[76:79], v[174:177], v[194:197], v[76:79]
	v_mfma_f32_16x16x32_bf16 v[100:103], v[166:169], v[212:215], v[100:103]
	v_mfma_f32_16x16x32_bf16 v[68:71], v[174:177], v[212:215], v[68:71]
	v_mfma_f32_16x16x32_bf16 v[92:95], v[166:169], v[220:223], v[92:95]
	v_mfma_f32_16x16x32_bf16 v[80:83], v[174:177], v[220:223], v[80:83]
	s_setprio 0
	s_barrier
	s_add_i32 s88, s88, s72
	v_lshl_add_u64 v[198:199], s[60:61], 0, v[150:151]
	s_mov_b32 m0, s88
	ds_read_b128 v[178:181], v185 offset:16384
	ds_read_b128 v[186:189], v185 offset:17408
	ds_read_b128 v[190:193], v185 offset:18432
	ds_read_b128 v[194:197], v185 offset:19456
	ds_read_b128 v[208:211], v185 offset:20480
	ds_read_b128 v[212:215], v185 offset:21504
	ds_read_b128 v[216:219], v185 offset:22528
	ds_read_b128 v[220:223], v185 offset:23552
	global_load_lds_dwordx4 v[198:199], off
	s_add_i32 m0, s88, 0x2000
	s_add_u32 s88, s60, 0x40000
	v_lshl_add_u64 v[204:205], s[60:61], 0, v[0:1]
	s_addc_u32 s89, s61, 0
	s_add_i32 s90, s90, s72
	global_load_lds_dwordx4 v[204:205], off
	v_lshl_add_u64 v[206:207], s[88:89], 0, v[150:151]
	s_mov_b32 m0, s90
	v_lshl_add_u64 v[224:225], vcc, 0, v[148:149]
	global_load_lds_dwordx4 v[206:207], off
	v_lshl_add_u64 v[206:207], s[88:89], 0, v[0:1]
	s_add_i32 m0, s90, 0x2000
	s_nop 0
	global_load_lds_dwordx4 v[206:207], off
	v_lshl_add_u64 v[206:207], vcc, 0, v[152:153]


	s_waitcnt vmcnt(6)
	s_waitcnt lgkmcnt(0)
	s_barrier
	s_setprio 1
	s_waitcnt lgkmcnt(0)
	v_mfma_f32_16x16x32_bf16 v[64:67], v[132:135], v[178:181], v[64:67]
	v_mfma_f32_16x16x32_bf16 v[56:59], v[140:143], v[178:181], v[56:59]
	v_mfma_f32_16x16x32_bf16 v[52:55], v[132:135], v[190:193], v[52:55]
	v_mfma_f32_16x16x32_bf16 v[20:23], v[140:143], v[190:193], v[20:23]
	v_mfma_f32_16x16x32_bf16 v[40:43], v[132:135], v[208:211], v[40:43]
	v_mfma_f32_16x16x32_bf16 v[8:11], v[140:143], v[208:211], v[8:11]
	v_mfma_f32_16x16x32_bf16 v[32:35], v[132:135], v[216:219], v[32:35]
	v_mfma_f32_16x16x32_bf16 v[24:27], v[140:143], v[216:219], v[24:27]
	v_mfma_f32_16x16x32_bf16 v[64:67], v[136:139], v[186:189], v[64:67]
	v_mfma_f32_16x16x32_bf16 v[56:59], v[144:147], v[186:189], v[56:59]
	v_mfma_f32_16x16x32_bf16 v[52:55], v[136:139], v[194:197], v[52:55]
	v_mfma_f32_16x16x32_bf16 v[20:23], v[144:147], v[194:197], v[20:23]
	v_mfma_f32_16x16x32_bf16 v[40:43], v[136:139], v[212:215], v[40:43]
	v_mfma_f32_16x16x32_bf16 v[8:11], v[144:147], v[212:215], v[8:11]
	v_mfma_f32_16x16x32_bf16 v[32:35], v[136:139], v[220:223], v[32:35]
	v_mfma_f32_16x16x32_bf16 v[24:27], v[144:147], v[220:223], v[24:27]
	s_setprio 0
	s_setprio 1
	v_mfma_f32_16x16x32_bf16 v[60:63], v[162:165], v[178:181], v[60:63]
	v_mfma_f32_16x16x32_bf16 v[48:51], v[170:173], v[178:181], v[48:51]
	v_mfma_f32_16x16x32_bf16 v[44:47], v[162:165], v[190:193], v[44:47]
	v_mfma_f32_16x16x32_bf16 v[12:15], v[170:173], v[190:193], v[12:15]
	v_mfma_f32_16x16x32_bf16 v[36:39], v[162:165], v[208:211], v[36:39]
	v_mfma_f32_16x16x32_bf16 v[4:7], v[170:173], v[208:211], v[4:7]
	v_mfma_f32_16x16x32_bf16 v[28:31], v[162:165], v[216:219], v[28:31]
	v_mfma_f32_16x16x32_bf16 v[16:19], v[170:173], v[216:219], v[16:19]
	v_mfma_f32_16x16x32_bf16 v[60:63], v[166:169], v[186:189], v[60:63]
	v_mfma_f32_16x16x32_bf16 v[48:51], v[174:177], v[186:189], v[48:51]
	v_mfma_f32_16x16x32_bf16 v[44:47], v[166:169], v[194:197], v[44:47]
	v_mfma_f32_16x16x32_bf16 v[12:15], v[174:177], v[194:197], v[12:15]
	v_mfma_f32_16x16x32_bf16 v[36:39], v[166:169], v[212:215], v[36:39]
	v_mfma_f32_16x16x32_bf16 v[4:7], v[174:177], v[212:215], v[4:7]
	v_mfma_f32_16x16x32_bf16 v[28:31], v[166:169], v[220:223], v[28:31]
	v_mfma_f32_16x16x32_bf16 v[16:19], v[174:177], v[220:223], v[16:19]
	s_setprio 0
	s_barrier
	s_add_i32 s90, 0, 0x18000
	v_add_u32_e32 v2, s90, v182
	s_add_i32 s91, 0, 0x1c000
	ds_read_b128 v[132:135], v2
	ds_read_b128 v[136:139], v2 offset:1024
	ds_read_b128 v[140:143], v2 offset:2048
	ds_read_b128 v[144:147], v2 offset:3072
	v_add_u32_e32 v2, s91, v182
	ds_read_b128 v[162:165], v2
	ds_read_b128 v[166:169], v2 offset:1024
	ds_read_b128 v[170:173], v2 offset:2048
	ds_read_b128 v[174:177], v2 offset:3072
	s_add_u32 s88, vcc_lo, 0x40000
	s_addc_u32 s89, vcc_hi, 0
	s_mov_b32 m0, s73
	s_nop 0
	global_load_lds_dwordx4 v[206:207], off
	s_mov_b32 m0, s74
	s_nop 0
	global_load_lds_dwordx4 v[224:225], off
	s_mov_b32 m0, s75
	v_lshl_add_u64 v[226:227], s[88:89], 0, v[152:153]
	ds_read_b128 v[178:181], v185 offset:32768
	ds_read_b128 v[186:189], v185 offset:33792
	ds_read_b128 v[190:193], v185 offset:34816
	ds_read_b128 v[194:197], v185 offset:35840
	ds_read_b128 v[208:211], v185 offset:36864
	ds_read_b128 v[212:215], v185 offset:37888
	ds_read_b128 v[216:219], v185 offset:38912
	ds_read_b128 v[220:223], v185 offset:39936
	global_load_lds_dwordx4 v[226:227], off
	v_lshl_add_u64 v[226:227], s[88:89], 0, v[148:149]
	s_mov_b32 m0, s76
	s_nop 0
	global_load_lds_dwordx4 v[226:227], off
	s_waitcnt vmcnt(8)
	s_waitcnt lgkmcnt(0)
	s_barrier
	s_setprio 1
	s_waitcnt lgkmcnt(0)
	v_mfma_f32_16x16x32_bf16 v[128:131], v[132:135], v[178:181], v[128:131]
	v_mfma_f32_16x16x32_bf16 v[120:123], v[140:143], v[178:181], v[120:123]
	v_mfma_f32_16x16x32_bf16 v[112:115], v[132:135], v[190:193], v[112:115]
	v_mfma_f32_16x16x32_bf16 v[84:87], v[140:143], v[190:193], v[84:87]
	v_mfma_f32_16x16x32_bf16 v[104:107], v[132:135], v[208:211], v[104:107]
	v_mfma_f32_16x16x32_bf16 v[72:75], v[140:143], v[208:211], v[72:75]
	v_mfma_f32_16x16x32_bf16 v[96:99], v[132:135], v[216:219], v[96:99]
	v_mfma_f32_16x16x32_bf16 v[88:91], v[140:143], v[216:219], v[88:91]
	v_mfma_f32_16x16x32_bf16 v[128:131], v[136:139], v[186:189], v[128:131]
	v_mfma_f32_16x16x32_bf16 v[120:123], v[144:147], v[186:189], v[120:123]
	v_mfma_f32_16x16x32_bf16 v[112:115], v[136:139], v[194:197], v[112:115]
	v_mfma_f32_16x16x32_bf16 v[84:87], v[144:147], v[194:197], v[84:87]
	v_mfma_f32_16x16x32_bf16 v[104:107], v[136:139], v[212:215], v[104:107]
	v_mfma_f32_16x16x32_bf16 v[72:75], v[144:147], v[212:215], v[72:75]
	v_mfma_f32_16x16x32_bf16 v[96:99], v[136:139], v[220:223], v[96:99]
	v_mfma_f32_16x16x32_bf16 v[88:91], v[144:147], v[220:223], v[88:91]
	s_setprio 0
	s_setprio 1
	v_mfma_f32_16x16x32_bf16 v[124:127], v[162:165], v[178:181], v[124:127]
	v_mfma_f32_16x16x32_bf16 v[116:119], v[170:173], v[178:181], v[116:119]
	v_mfma_f32_16x16x32_bf16 v[108:111], v[162:165], v[190:193], v[108:111]
	v_mfma_f32_16x16x32_bf16 v[76:79], v[170:173], v[190:193], v[76:79]
	v_mfma_f32_16x16x32_bf16 v[100:103], v[162:165], v[208:211], v[100:103]
	v_mfma_f32_16x16x32_bf16 v[68:71], v[170:173], v[208:211], v[68:71]
	v_mfma_f32_16x16x32_bf16 v[92:95], v[162:165], v[216:219], v[92:95]
	v_mfma_f32_16x16x32_bf16 v[80:83], v[170:173], v[216:219], v[80:83]
	v_mfma_f32_16x16x32_bf16 v[124:127], v[166:169], v[186:189], v[124:127]
	v_mfma_f32_16x16x32_bf16 v[116:119], v[174:177], v[186:189], v[116:119]
	v_mfma_f32_16x16x32_bf16 v[108:111], v[166:169], v[194:197], v[108:111]
	v_mfma_f32_16x16x32_bf16 v[76:79], v[174:177], v[194:197], v[76:79]
	v_mfma_f32_16x16x32_bf16 v[100:103], v[166:169], v[212:215], v[100:103]
	v_mfma_f32_16x16x32_bf16 v[68:71], v[174:177], v[212:215], v[68:71]
	v_mfma_f32_16x16x32_bf16 v[92:95], v[166:169], v[220:223], v[92:95]
	v_mfma_f32_16x16x32_bf16 v[80:83], v[174:177], v[220:223], v[80:83]
	s_setprio 0
	s_barrier
	s_add_i32 s88, s90, s72
	v_lshl_add_u64 v[198:199], v[198:199], 0, s[12:13]
	s_mov_b32 m0, s88
	ds_read_b128 v[178:181], v185 offset:49152
	ds_read_b128 v[186:189], v185 offset:50176
	ds_read_b128 v[190:193], v185 offset:51200
	ds_read_b128 v[194:197], v185 offset:52224
	ds_read_b128 v[208:211], v185 offset:53248
	ds_read_b128 v[212:215], v185 offset:54272
	ds_read_b128 v[216:219], v185 offset:55296
	ds_read_b128 v[220:223], v185 offset:56320
	global_load_lds_dwordx4 v[198:199], off
	s_add_i32 m0, s88, 0x2000
	s_add_u32 s60, s60, 0x40080
	v_lshl_add_u64 v[198:199], v[204:205], 0, s[12:13]
	s_addc_u32 s61, s61, 0
	s_add_i32 s88, s91, s72
	global_load_lds_dwordx4 v[198:199], off
	v_lshl_add_u64 v[198:199], s[60:61], 0, v[150:151]
	s_mov_b32 m0, s88
	s_nop 0
	global_load_lds_dwordx4 v[198:199], off
	v_lshl_add_u64 v[198:199], s[60:61], 0, v[0:1]
	s_add_i32 m0, s88, 0x2000
	s_nop 0
	global_load_lds_dwordx4 v[198:199], off


	s_waitcnt vmcnt(6)
	s_waitcnt lgkmcnt(0)
	s_barrier
	s_setprio 1
	s_waitcnt lgkmcnt(0)
	v_mfma_f32_16x16x32_bf16 v[64:67], v[132:135], v[178:181], v[64:67]
	v_mfma_f32_16x16x32_bf16 v[56:59], v[140:143], v[178:181], v[56:59]
	v_mfma_f32_16x16x32_bf16 v[52:55], v[132:135], v[190:193], v[52:55]
	v_mfma_f32_16x16x32_bf16 v[20:23], v[140:143], v[190:193], v[20:23]
	v_mfma_f32_16x16x32_bf16 v[40:43], v[132:135], v[208:211], v[40:43]
	v_mfma_f32_16x16x32_bf16 v[8:11], v[140:143], v[208:211], v[8:11]
	v_mfma_f32_16x16x32_bf16 v[32:35], v[132:135], v[216:219], v[32:35]
	v_mfma_f32_16x16x32_bf16 v[24:27], v[140:143], v[216:219], v[24:27]
	v_mfma_f32_16x16x32_bf16 v[64:67], v[136:139], v[186:189], v[64:67]
	v_mfma_f32_16x16x32_bf16 v[56:59], v[144:147], v[186:189], v[56:59]
	v_mfma_f32_16x16x32_bf16 v[52:55], v[136:139], v[194:197], v[52:55]
	v_mfma_f32_16x16x32_bf16 v[20:23], v[144:147], v[194:197], v[20:23]
	v_mfma_f32_16x16x32_bf16 v[40:43], v[136:139], v[212:215], v[40:43]
	v_mfma_f32_16x16x32_bf16 v[8:11], v[144:147], v[212:215], v[8:11]
	v_mfma_f32_16x16x32_bf16 v[32:35], v[136:139], v[220:223], v[32:35]
	v_mfma_f32_16x16x32_bf16 v[24:27], v[144:147], v[220:223], v[24:27]
	s_setprio 0
	s_setprio 1
	v_mfma_f32_16x16x32_bf16 v[60:63], v[162:165], v[178:181], v[60:63]
	v_mfma_f32_16x16x32_bf16 v[48:51], v[170:173], v[178:181], v[48:51]
	v_mfma_f32_16x16x32_bf16 v[44:47], v[162:165], v[190:193], v[44:47]
	v_mfma_f32_16x16x32_bf16 v[12:15], v[170:173], v[190:193], v[12:15]
	v_mfma_f32_16x16x32_bf16 v[36:39], v[162:165], v[208:211], v[36:39]
	v_mfma_f32_16x16x32_bf16 v[4:7], v[170:173], v[208:211], v[4:7]
	v_mfma_f32_16x16x32_bf16 v[28:31], v[162:165], v[216:219], v[28:31]
	v_mfma_f32_16x16x32_bf16 v[16:19], v[170:173], v[216:219], v[16:19]
	v_mfma_f32_16x16x32_bf16 v[60:63], v[166:169], v[186:189], v[60:63]
	v_mfma_f32_16x16x32_bf16 v[48:51], v[174:177], v[186:189], v[48:51]
	v_mfma_f32_16x16x32_bf16 v[44:47], v[166:169], v[194:197], v[44:47]
	v_mfma_f32_16x16x32_bf16 v[12:15], v[174:177], v[194:197], v[12:15]
	v_mfma_f32_16x16x32_bf16 v[36:39], v[166:169], v[212:215], v[36:39]
	v_mfma_f32_16x16x32_bf16 v[4:7], v[174:177], v[212:215], v[4:7]
	v_mfma_f32_16x16x32_bf16 v[28:31], v[166:169], v[220:223], v[28:31]
	v_mfma_f32_16x16x32_bf16 v[16:19], v[174:177], v[220:223], v[16:19]
	s_setprio 0
	s_barrier
	s_add_i32 s87, s87, 2
	s_add_u32 s48, s48, 0x100
	s_addc_u32 s49, s49, 0
	s_add_u32 s85, s85, 0x100
	s_addc_u32 s86, s86, 0
	s_cmp_gt_u32 s87, 13
	s_cbranch_scc0 .LBB0_94
	s_and_b64 vcc, exec, s[20:21]
	s_cbranch_vccz .LBB0_97
	s_barrier

.LBB0_685:
	s_add_u32 s82, s46, 0xfff80000
	s_addc_u32 s83, s47, -1
	v_lshl_add_u64 v[200:201], s[82:83], 0, v[134:135]
	s_mov_b32 m0, s71
	s_nop 0
	global_load_lds_dwordx4 v[200:201], off
	v_lshl_add_u64 v[200:201], s[82:83], 0, v[132:133]
	s_mov_b32 m0, s72
	s_nop 0
	global_load_lds_dwordx4 v[200:201], off
	s_add_u32 s48, s46, 0xfff80080
	s_addc_u32 s49, s47, -1
	s_add_i32 s81, 0, 0x10000
	s_cmp_eq_u32 s80, 28
	s_cselect_b32 s51, s35, s49
	s_cselect_b32 s50, s76, s48
	s_cselect_b32 s49, s21, s79
	s_cselect_b32 s48, s77, s78
	s_add_i32 s84, 0, 0x14000
	v_add_u32_e32 v156, s81, v149
	v_add_u32_e32 v172, s84, v149
	ds_read_b128 v[140:143], v156
	ds_read_b128 v[144:147], v156 offset:1024
	ds_read_b128 v[152:155], v156 offset:2048
	ds_read_b128 v[156:159], v156 offset:3072
	ds_read_b128 v[160:163], v172
	ds_read_b128 v[164:167], v172 offset:1024
	ds_read_b128 v[168:171], v172 offset:2048
	ds_read_b128 v[172:175], v172 offset:3072
	v_lshl_add_u64 v[200:201], s[46:47], 0, v[136:137]
	s_add_i32 m0, s59, 0xc000
	ds_read_b128 v[176:179], v151
	ds_read_b128 v[180:183], v151 offset:1024
	ds_read_b128 v[184:187], v151 offset:2048
	ds_read_b128 v[188:191], v151 offset:3072
	ds_read_b128 v[192:195], v151 offset:4096
	ds_read_b128 v[196:199], v151 offset:5120
	ds_read_b128 v[204:207], v151 offset:6144
	ds_read_b128 v[208:211], v151 offset:7168
	global_load_lds_dwordx4 v[200:201], off
	v_lshl_add_u64 v[200:201], s[46:47], 0, v[138:139]
	s_add_i32 m0, s59, 0xe000
	s_nop 0
	global_load_lds_dwordx4 v[200:201], off
	s_waitcnt vmcnt(8)
	s_waitcnt lgkmcnt(0)
	s_barrier
	s_setprio 1
	s_waitcnt lgkmcnt(0)
	v_mfma_f32_16x16x32_bf16 v[128:131], v[140:143], v[176:179], v[128:131]
	v_mfma_f32_16x16x32_bf16 v[124:127], v[152:155], v[176:179], v[124:127]
	v_mfma_f32_16x16x32_bf16 v[112:115], v[140:143], v[184:187], v[112:115]
	v_mfma_f32_16x16x32_bf16 v[108:111], v[152:155], v[184:187], v[108:111]
	v_mfma_f32_16x16x32_bf16 v[96:99], v[140:143], v[192:195], v[96:99]
	v_mfma_f32_16x16x32_bf16 v[92:95], v[152:155], v[192:195], v[92:95]
	v_mfma_f32_16x16x32_bf16 v[80:83], v[140:143], v[204:207], v[80:83]
	v_mfma_f32_16x16x32_bf16 v[76:79], v[152:155], v[204:207], v[76:79]
	v_mfma_f32_16x16x32_bf16 v[128:131], v[144:147], v[180:183], v[128:131]
	v_mfma_f32_16x16x32_bf16 v[124:127], v[156:159], v[180:183], v[124:127]
	v_mfma_f32_16x16x32_bf16 v[112:115], v[144:147], v[188:191], v[112:115]
	v_mfma_f32_16x16x32_bf16 v[108:111], v[156:159], v[188:191], v[108:111]
	v_mfma_f32_16x16x32_bf16 v[96:99], v[144:147], v[196:199], v[96:99]
	v_mfma_f32_16x16x32_bf16 v[92:95], v[156:159], v[196:199], v[92:95]
	v_mfma_f32_16x16x32_bf16 v[80:83], v[144:147], v[208:211], v[80:83]
	v_mfma_f32_16x16x32_bf16 v[76:79], v[156:159], v[208:211], v[76:79]
	s_setprio 0
	s_setprio 1
	v_mfma_f32_16x16x32_bf16 v[120:123], v[160:163], v[176:179], v[120:123]
	v_mfma_f32_16x16x32_bf16 v[116:119], v[168:171], v[176:179], v[116:119]
	v_mfma_f32_16x16x32_bf16 v[104:107], v[160:163], v[184:187], v[104:107]
	v_mfma_f32_16x16x32_bf16 v[100:103], v[168:171], v[184:187], v[100:103]
	v_mfma_f32_16x16x32_bf16 v[88:91], v[160:163], v[192:195], v[88:91]
	v_mfma_f32_16x16x32_bf16 v[84:87], v[168:171], v[192:195], v[84:87]
	v_mfma_f32_16x16x32_bf16 v[72:75], v[160:163], v[204:207], v[72:75]
	v_mfma_f32_16x16x32_bf16 v[68:71], v[168:171], v[204:207], v[68:71]
	v_mfma_f32_16x16x32_bf16 v[120:123], v[164:167], v[180:183], v[120:123]
	v_mfma_f32_16x16x32_bf16 v[116:119], v[172:175], v[180:183], v[116:119]
	v_mfma_f32_16x16x32_bf16 v[104:107], v[164:167], v[188:191], v[104:107]
	v_mfma_f32_16x16x32_bf16 v[100:103], v[172:175], v[188:191], v[100:103]
	v_mfma_f32_16x16x32_bf16 v[88:91], v[164:167], v[196:199], v[88:91]
	v_mfma_f32_16x16x32_bf16 v[84:87], v[172:175], v[196:199], v[84:87]
	v_mfma_f32_16x16x32_bf16 v[72:75], v[164:167], v[208:211], v[72:75]
	v_mfma_f32_16x16x32_bf16 v[68:71], v[172:175], v[208:211], v[68:71]
	s_setprio 0
	s_barrier
	s_add_i32 s81, s81, s52
	v_lshl_add_u64 v[200:201], s[48:49], 0, v[2:3]
	s_mov_b32 m0, s81
	ds_read_b128 v[176:179], v151 offset:16384
	ds_read_b128 v[180:183], v151 offset:17408
	ds_read_b128 v[184:187], v151 offset:18432
	ds_read_b128 v[188:191], v151 offset:19456
	ds_read_b128 v[192:195], v151 offset:20480
	ds_read_b128 v[196:199], v151 offset:21504
	ds_read_b128 v[204:207], v151 offset:22528
	ds_read_b128 v[208:211], v151 offset:23552
	global_load_lds_dwordx4 v[200:201], off
	s_add_i32 m0, s81, 0x2000
	s_add_u32 s82, s48, 0x80000
	v_lshl_add_u64 v[212:213], s[48:49], 0, v[0:1]
	s_addc_u32 s83, s49, 0
	s_add_i32 s81, s84, s52
	global_load_lds_dwordx4 v[212:213], off
	v_lshl_add_u64 v[214:215], s[82:83], 0, v[2:3]
	s_mov_b32 m0, s81
	v_lshl_add_u64 v[216:217], s[50:51], 0, v[132:133]
	global_load_lds_dwordx4 v[214:215], off
	v_lshl_add_u64 v[214:215], s[82:83], 0, v[0:1]
	s_add_i32 m0, s81, 0x2000
	s_nop 0
	global_load_lds_dwordx4 v[214:215], off
	v_lshl_add_u64 v[214:215], s[50:51], 0, v[134:135]


	s_waitcnt vmcnt(6)
	s_waitcnt lgkmcnt(0)
	s_barrier
	s_setprio 1
	s_waitcnt lgkmcnt(0)
	v_mfma_f32_16x16x32_bf16 v[64:67], v[140:143], v[176:179], v[64:67]
	v_mfma_f32_16x16x32_bf16 v[60:63], v[152:155], v[176:179], v[60:63]
	v_mfma_f32_16x16x32_bf16 v[48:51], v[140:143], v[184:187], v[48:51]
	v_mfma_f32_16x16x32_bf16 v[44:47], v[152:155], v[184:187], v[44:47]
	v_mfma_f32_16x16x32_bf16 v[32:35], v[140:143], v[192:195], v[32:35]
	v_mfma_f32_16x16x32_bf16 v[28:31], v[152:155], v[192:195], v[28:31]
	v_mfma_f32_16x16x32_bf16 v[16:19], v[140:143], v[204:207], v[16:19]
	v_mfma_f32_16x16x32_bf16 v[12:15], v[152:155], v[204:207], v[12:15]
	v_mfma_f32_16x16x32_bf16 v[64:67], v[144:147], v[180:183], v[64:67]
	v_mfma_f32_16x16x32_bf16 v[60:63], v[156:159], v[180:183], v[60:63]
	v_mfma_f32_16x16x32_bf16 v[48:51], v[144:147], v[188:191], v[48:51]
	v_mfma_f32_16x16x32_bf16 v[44:47], v[156:159], v[188:191], v[44:47]
	v_mfma_f32_16x16x32_bf16 v[32:35], v[144:147], v[196:199], v[32:35]
	v_mfma_f32_16x16x32_bf16 v[28:31], v[156:159], v[196:199], v[28:31]
	v_mfma_f32_16x16x32_bf16 v[16:19], v[144:147], v[208:211], v[16:19]
	v_mfma_f32_16x16x32_bf16 v[12:15], v[156:159], v[208:211], v[12:15]
	s_setprio 0
	s_setprio 1
	v_mfma_f32_16x16x32_bf16 v[56:59], v[160:163], v[176:179], v[56:59]
	v_mfma_f32_16x16x32_bf16 v[52:55], v[168:171], v[176:179], v[52:55]
	v_mfma_f32_16x16x32_bf16 v[40:43], v[160:163], v[184:187], v[40:43]
	v_mfma_f32_16x16x32_bf16 v[36:39], v[168:171], v[184:187], v[36:39]
	v_mfma_f32_16x16x32_bf16 v[24:27], v[160:163], v[192:195], v[24:27]
	v_mfma_f32_16x16x32_bf16 v[20:23], v[168:171], v[192:195], v[20:23]
	v_mfma_f32_16x16x32_bf16 v[8:11], v[160:163], v[204:207], v[8:11]
	v_mfma_f32_16x16x32_bf16 v[4:7], v[168:171], v[204:207], v[4:7]
	v_mfma_f32_16x16x32_bf16 v[56:59], v[164:167], v[180:183], v[56:59]
	v_mfma_f32_16x16x32_bf16 v[52:55], v[172:175], v[180:183], v[52:55]
	v_mfma_f32_16x16x32_bf16 v[40:43], v[164:167], v[188:191], v[40:43]
	v_mfma_f32_16x16x32_bf16 v[36:39], v[172:175], v[188:191], v[36:39]
	v_mfma_f32_16x16x32_bf16 v[24:27], v[164:167], v[196:199], v[24:27]
	v_mfma_f32_16x16x32_bf16 v[20:23], v[172:175], v[196:199], v[20:23]
	v_mfma_f32_16x16x32_bf16 v[8:11], v[164:167], v[208:211], v[8:11]
	v_mfma_f32_16x16x32_bf16 v[4:7], v[172:175], v[208:211], v[4:7]
	s_setprio 0
	s_barrier
	s_add_i32 s81, 0, 0x18000
	s_add_i32 s82, 0, 0x1c000
	v_add_u32_e32 v156, s81, v149
	v_add_u32_e32 v172, s82, v149
	ds_read_b128 v[140:143], v156
	ds_read_b128 v[144:147], v156 offset:1024
	ds_read_b128 v[152:155], v156 offset:2048
	ds_read_b128 v[156:159], v156 offset:3072
	ds_read_b128 v[160:163], v172
	ds_read_b128 v[164:167], v172 offset:1024
	ds_read_b128 v[168:171], v172 offset:2048
	ds_read_b128 v[172:175], v172 offset:3072
	s_add_u32 s50, s50, 0x80000
	s_addc_u32 s51, s51, 0
	s_mov_b32 m0, s59
	s_nop 0
	global_load_lds_dwordx4 v[214:215], off
	s_mov_b32 m0, s60
	s_nop 0
	global_load_lds_dwordx4 v[216:217], off
	s_mov_b32 m0, s61
	v_lshl_add_u64 v[218:219], s[50:51], 0, v[134:135]
	ds_read_b128 v[176:179], v151 offset:32768
	ds_read_b128 v[180:183], v151 offset:33792
	ds_read_b128 v[184:187], v151 offset:34816
	ds_read_b128 v[188:191], v151 offset:35840
	ds_read_b128 v[192:195], v151 offset:36864
	ds_read_b128 v[196:199], v151 offset:37888
	ds_read_b128 v[204:207], v151 offset:38912
	ds_read_b128 v[208:211], v151 offset:39936
	global_load_lds_dwordx4 v[218:219], off
	v_lshl_add_u64 v[218:219], s[50:51], 0, v[132:133]
	s_mov_b32 m0, s70
	s_nop 0
	global_load_lds_dwordx4 v[218:219], off
	s_waitcnt vmcnt(8)
	s_waitcnt lgkmcnt(0)
	s_barrier
	s_setprio 1
	s_waitcnt lgkmcnt(0)
	v_mfma_f32_16x16x32_bf16 v[128:131], v[140:143], v[176:179], v[128:131]
	v_mfma_f32_16x16x32_bf16 v[124:127], v[152:155], v[176:179], v[124:127]
	v_mfma_f32_16x16x32_bf16 v[112:115], v[140:143], v[184:187], v[112:115]
	v_mfma_f32_16x16x32_bf16 v[108:111], v[152:155], v[184:187], v[108:111]
	v_mfma_f32_16x16x32_bf16 v[96:99], v[140:143], v[192:195], v[96:99]
	v_mfma_f32_16x16x32_bf16 v[92:95], v[152:155], v[192:195], v[92:95]
	v_mfma_f32_16x16x32_bf16 v[80:83], v[140:143], v[204:207], v[80:83]
	v_mfma_f32_16x16x32_bf16 v[76:79], v[152:155], v[204:207], v[76:79]
	v_mfma_f32_16x16x32_bf16 v[128:131], v[144:147], v[180:183], v[128:131]
	v_mfma_f32_16x16x32_bf16 v[124:127], v[156:159], v[180:183], v[124:127]
	v_mfma_f32_16x16x32_bf16 v[112:115], v[144:147], v[188:191], v[112:115]
	v_mfma_f32_16x16x32_bf16 v[108:111], v[156:159], v[188:191], v[108:111]
	v_mfma_f32_16x16x32_bf16 v[96:99], v[144:147], v[196:199], v[96:99]
	v_mfma_f32_16x16x32_bf16 v[92:95], v[156:159], v[196:199], v[92:95]
	v_mfma_f32_16x16x32_bf16 v[80:83], v[144:147], v[208:211], v[80:83]
	v_mfma_f32_16x16x32_bf16 v[76:79], v[156:159], v[208:211], v[76:79]
	s_setprio 0
	s_setprio 1
	v_mfma_f32_16x16x32_bf16 v[120:123], v[160:163], v[176:179], v[120:123]
	v_mfma_f32_16x16x32_bf16 v[116:119], v[168:171], v[176:179], v[116:119]
	v_mfma_f32_16x16x32_bf16 v[104:107], v[160:163], v[184:187], v[104:107]
	v_mfma_f32_16x16x32_bf16 v[100:103], v[168:171], v[184:187], v[100:103]
	v_mfma_f32_16x16x32_bf16 v[88:91], v[160:163], v[192:195], v[88:91]
	v_mfma_f32_16x16x32_bf16 v[84:87], v[168:171], v[192:195], v[84:87]
	v_mfma_f32_16x16x32_bf16 v[72:75], v[160:163], v[204:207], v[72:75]
	v_mfma_f32_16x16x32_bf16 v[68:71], v[168:171], v[204:207], v[68:71]
	v_mfma_f32_16x16x32_bf16 v[120:123], v[164:167], v[180:183], v[120:123]
	v_mfma_f32_16x16x32_bf16 v[116:119], v[172:175], v[180:183], v[116:119]
	v_mfma_f32_16x16x32_bf16 v[104:107], v[164:167], v[188:191], v[104:107]
	v_mfma_f32_16x16x32_bf16 v[100:103], v[172:175], v[188:191], v[100:103]
	v_mfma_f32_16x16x32_bf16 v[88:91], v[164:167], v[196:199], v[88:91]
	v_mfma_f32_16x16x32_bf16 v[84:87], v[172:175], v[196:199], v[84:87]
	v_mfma_f32_16x16x32_bf16 v[72:75], v[164:167], v[208:211], v[72:75]
	v_mfma_f32_16x16x32_bf16 v[68:71], v[172:175], v[208:211], v[68:71]
	s_setprio 0
	s_barrier
	s_add_i32 s50, s81, s52
	v_lshl_add_u64 v[200:201], v[200:201], 0, s[12:13]
	s_mov_b32 m0, s50
	ds_read_b128 v[176:179], v151 offset:49152
	ds_read_b128 v[180:183], v151 offset:50176
	ds_read_b128 v[184:187], v151 offset:51200
	ds_read_b128 v[188:191], v151 offset:52224
	ds_read_b128 v[192:195], v151 offset:53248
	ds_read_b128 v[196:199], v151 offset:54272
	ds_read_b128 v[204:207], v151 offset:55296
	ds_read_b128 v[208:211], v151 offset:56320
	global_load_lds_dwordx4 v[200:201], off
	s_add_i32 m0, s50, 0x2000
	s_add_u32 s48, s48, 0x80080
	v_lshl_add_u64 v[200:201], v[212:213], 0, s[12:13]
	s_addc_u32 s49, s49, 0
	s_add_i32 s50, s82, s52
	global_load_lds_dwordx4 v[200:201], off
	v_lshl_add_u64 v[200:201], s[48:49], 0, v[2:3]
	s_mov_b32 m0, s50
	s_nop 0
	global_load_lds_dwordx4 v[200:201], off
	v_lshl_add_u64 v[200:201], s[48:49], 0, v[0:1]
	s_add_i32 m0, s50, 0x2000
	s_nop 0
	global_load_lds_dwordx4 v[200:201], off


	s_waitcnt vmcnt(6)
	s_waitcnt lgkmcnt(0)
	s_barrier
	s_setprio 1
	s_waitcnt lgkmcnt(0)
	v_mfma_f32_16x16x32_bf16 v[64:67], v[140:143], v[176:179], v[64:67]
	v_mfma_f32_16x16x32_bf16 v[60:63], v[152:155], v[176:179], v[60:63]
	v_mfma_f32_16x16x32_bf16 v[48:51], v[140:143], v[184:187], v[48:51]
	v_mfma_f32_16x16x32_bf16 v[44:47], v[152:155], v[184:187], v[44:47]
	v_mfma_f32_16x16x32_bf16 v[32:35], v[140:143], v[192:195], v[32:35]
	v_mfma_f32_16x16x32_bf16 v[28:31], v[152:155], v[192:195], v[28:31]
	v_mfma_f32_16x16x32_bf16 v[16:19], v[140:143], v[204:207], v[16:19]
	v_mfma_f32_16x16x32_bf16 v[12:15], v[152:155], v[204:207], v[12:15]
	v_mfma_f32_16x16x32_bf16 v[64:67], v[144:147], v[180:183], v[64:67]
	v_mfma_f32_16x16x32_bf16 v[60:63], v[156:159], v[180:183], v[60:63]
	v_mfma_f32_16x16x32_bf16 v[48:51], v[144:147], v[188:191], v[48:51]
	v_mfma_f32_16x16x32_bf16 v[44:47], v[156:159], v[188:191], v[44:47]
	v_mfma_f32_16x16x32_bf16 v[32:35], v[144:147], v[196:199], v[32:35]
	v_mfma_f32_16x16x32_bf16 v[28:31], v[156:159], v[196:199], v[28:31]
	v_mfma_f32_16x16x32_bf16 v[16:19], v[144:147], v[208:211], v[16:19]
	v_mfma_f32_16x16x32_bf16 v[12:15], v[156:159], v[208:211], v[12:15]
	s_setprio 0
	s_setprio 1
	v_mfma_f32_16x16x32_bf16 v[56:59], v[160:163], v[176:179], v[56:59]
	v_mfma_f32_16x16x32_bf16 v[52:55], v[168:171], v[176:179], v[52:55]
	v_mfma_f32_16x16x32_bf16 v[40:43], v[160:163], v[184:187], v[40:43]
	v_mfma_f32_16x16x32_bf16 v[36:39], v[168:171], v[184:187], v[36:39]
	v_mfma_f32_16x16x32_bf16 v[24:27], v[160:163], v[192:195], v[24:27]
	v_mfma_f32_16x16x32_bf16 v[20:23], v[168:171], v[192:195], v[20:23]
	v_mfma_f32_16x16x32_bf16 v[8:11], v[160:163], v[204:207], v[8:11]
	v_mfma_f32_16x16x32_bf16 v[4:7], v[168:171], v[204:207], v[4:7]
	v_mfma_f32_16x16x32_bf16 v[56:59], v[164:167], v[180:183], v[56:59]
	v_mfma_f32_16x16x32_bf16 v[52:55], v[172:175], v[180:183], v[52:55]
	v_mfma_f32_16x16x32_bf16 v[40:43], v[164:167], v[188:191], v[40:43]
	v_mfma_f32_16x16x32_bf16 v[36:39], v[172:175], v[188:191], v[36:39]
	v_mfma_f32_16x16x32_bf16 v[24:27], v[164:167], v[196:199], v[24:27]
	v_mfma_f32_16x16x32_bf16 v[20:23], v[172:175], v[196:199], v[20:23]
	v_mfma_f32_16x16x32_bf16 v[8:11], v[164:167], v[208:211], v[8:11]
	v_mfma_f32_16x16x32_bf16 v[4:7], v[172:175], v[208:211], v[4:7]
	s_setprio 0
	s_barrier
	s_add_i32 s80, s80, 2
	s_add_u32 s46, s46, 0x100
	s_addc_u32 s47, s47, 0
	s_add_u32 s78, s78, 0x100
	s_addc_u32 s79, s79, 0
	s_cmp_gt_u32 s80, 29
	s_cbranch_scc0 .LBB0_685
	v_readlane_b32 s78, v254, 48
	v_readlane_b32 s80, v254, 50
	s_and_b64 vcc, exec, s[10:11]
	v_readlane_b32 s79, v254, 49
	v_readlane_b32 s81, v254, 51
	v_readlane_b32 s76, v254, 62
	v_readlane_b32 s77, v254, 63
	s_cbranch_vccz .LBB0_688
	s_barrier
